# scan: kk/wk stored interleaved in the LDS step records (pair of dot products from 4 packed FMAs), per-row pair scalars v0,v1,beta,kappa in one 16-B slot (one ds_read_b128 instead of three reads)
# speedup vs baseline: 1.0139x; 1.0139x over previous
; #define LAS __attribute__((address_space(3)))
; #define SC_BAR() do { asm volatile("s_waitcnt lgkmcnt(0)" ::: "memory"); __builtin_amdgcn_s_barrier(); asm volatile("" ::: "memory"); } while (0)
; __device__ __forceinline__ void scan_phase(const Params& P, LAS unsigned char* lds, int tid, int wid, int lane) {
;     constexpr int NCK = (LPOS + TC - 1) / TC;
;     typedef float f32x2v __attribute__((ext_vector_type(2)));
;     const int vcu_ = (gridDim.x % 8 == 0) ? ((int)blockIdx.x % 8) * ((int)gridDim.x / 8) + (int)blockIdx.x / 8 : (int)blockIdx.x;
;     for (int it = vcu_; it < 256; it += gridDim.x) {
;         const int bh = it >> 2, rg = it & 3, b = bh >> 3, h = bh & 7;
;         f32x4 S = (f32x4){0.f, 0.f, 0.f, 0.f};
;         const int jq = lane & 15, il = 4 * wid + (lane >> 4), ll = tid - 256;
;         ScanRegs R;
;         SC_BAR();
;         if (wid >= 4) { scan_gload(P, R, b, h, rg, 0, ll); scan_cvt_write(P, h, R, lds, ll); scan_gload(P, R, b, h, rg, 1, ll); }
;         SC_BAR();
;         for (int ck = 0; ck < NCK; ++ck) {
;             const int nsteps = (LPOS - TC * ck) < TC ? (LPOS - TC * ck) : TC;
;             if (wid >= 4) {
;                 if (ck + 1 < NCK) { scan_cvt_write(P, h, R, lds + ((ck + 1) & 1) * SBUF, ll); scan_gload(P, R, b, h, rg, ck + 2 < NCK ? ck + 2 : NCK - 1, ll); }
;                 if (ck > 0) scan_flush(P, lds + YOFF + ((ck - 1) & 1) * 2048, b, h, rg, ck - 1, ll);
;             } else {
;                 const LAS unsigned char* buf = lds + (ck & 1) * SBUF + jq * 16; const LAS unsigned char* vbuf = lds + (ck & 1) * SBUF + 1280 + il * 4; const LAS unsigned char* sbuf = lds + (ck & 1) * SBUF + 1600;
.LBB0_833:
	s_cmp_gt_i32 s88, 8
	s_cselect_b64 s[0:1], -1, 0
	s_cmp_lt_i32 s89, 9
	s_cselect_b64 s[2:3], -1, 0
	s_or_b64 s[0:1], s[0:1], s[2:3]
	s_and_b64 vcc, exec, s[0:1]
	s_cbranch_vccnz .LBB0_938
	s_ashr_i32 s2, s33, 31
	s_lshr_b32 s2, s2, 29
	s_add_i32 s2, s33, s2
	s_and_b32 s3, s2, -8
	s_ashr_i32 s1, s96, 3
	s_sub_i32 s3, s33, s3
	s_mul_i32 s1, s1, s3
	s_ashr_i32 s2, s2, 3
	v_writelane_b32 v254, s91, 27
	s_and_b32 s0, s96, 7
	s_add_i32 s1, s1, s2
	v_writelane_b32 v254, s90, 28
	s_cmp_eq_u32 s0, 0
	v_writelane_b32 v254, s65, 29
	s_cselect_b32 s16, s1, s33
	v_writelane_b32 v254, s66, 30
	s_cmpk_gt_i32 s16, 0xff
	s_mov_b32 s1, 0
	v_writelane_b32 v254, s67, 31
	s_cbranch_scc1 .LBB0_884
	s_waitcnt lgkmcnt(0)
	v_add_u32_e32 v1, 0xffffff00, v209
	v_ashrrev_i32_e32 v2, 3, v1
	v_and_b32_e32 v107, -2, v2
	v_add_u32_e32 v5, -1, v107
	v_cmp_gt_u32_e64 s[8:9], 16, v5
	v_min_u32_e32 v113, 0x80f, v5
	v_add_u32_e32 v5, 31, v107
	v_writelane_b32 v254, s8, 32
	v_lshlrev_b32_e32 v3, 2, v1
	s_movk_i32 s0, 0x650
	v_writelane_b32 v254, s9, 33
	v_cmp_gt_u32_e64 s[8:9], 16, v2
	v_ashrrev_i32_e32 v122, 2, v1
	v_lshlrev_b32_e32 v1, 4, v1
	v_writelane_b32 v254, s8, 34
	v_and_b32_e32 v46, 60, v3
	v_or_b32_e32 v4, 1, v2
	v_writelane_b32 v254, s9, 35
	v_cmp_gt_i32_e64 s[8:9], 15, v107
	v_cmp_lt_i32_e64 s[6:7], 1, v2
	v_cmp_lt_i32_e64 s[10:11], -1, v2
	v_writelane_b32 v254, s8, 36
	v_and_b32_e32 v2, 12, v3
	v_mad_i32_i24 v121, v107, s0, 0
	v_writelane_b32 v254, s9, 37
	s_movk_i32 s8, 0x180
	v_cmp_gt_u32_e64 s[22:23], s8, v209
	v_cmp_gt_u32_e64 s[8:9], 16, v5
	v_mad_i32_i24 v3, v122, s0, 0
	v_and_b32_e32 v124, 48, v1
	v_add_u32_e32 v1, 32, v107
	s_movk_i32 s0, 0xffe0
	v_writelane_b32 v254, s8, 38
	v_cmp_lt_i32_e64 s[28:29], s0, v107
	s_movk_i32 s0, 0xffdf
	v_writelane_b32 v254, s9, 39
	v_cmp_gt_u32_e64 s[8:9], 16, v1
	v_cmp_lt_i32_e64 s[34:35], s0, v107
	s_movk_i32 s0, 0xffde
	v_writelane_b32 v254, s8, 40
	v_min_i32_e32 v125, 0x80f, v1
	v_min_u32_e32 v129, 0x80f, v1
	v_writelane_b32 v254, s9, 41
	v_cmp_lt_i32_e64 s[38:39], s0, v107
	s_movk_i32 s0, 0xffef
	v_lshrrev_b32_e32 v1, 2, v208
	s_cmpk_gt_u32 s92, 0xff
	v_cmp_gt_i32_e64 s[40:41], s0, v107
	v_and_b32_e32 v1, 12, v1
	v_readlane_b32 s0, v254, 27
	s_cselect_b64 s[72:73], -1, 0
	v_and_b32_e32 v47, 15, v209
	v_lshl_or_b32 v134, s0, 4, v1
	s_add_i32 s0, 0, 0x19400
	v_mov_b32_e32 v0, 0
	s_add_u32 s74, s86, 0x4d00000
	v_lshlrev_b32_e32 v48, 4, v47
	v_mov_b32_e32 v49, v0
	s_addc_u32 s75, s87, 0
	v_lshl_add_u64 v[50:51], s[76:77], 0, v[48:49]
	s_add_u32 s76, s86, 0xc740000
	s_addc_u32 s77, s87, 0
	s_add_u32 s78, s86, 0xd780000
	s_addc_u32 s79, s87, 0
	s_add_u32 s80, s86, 0xe7c0000
	v_min_i32_e32 v112, 0x80f, v4
	v_cmp_gt_i32_e64 s[4:5], 16, v4
	v_min_u32_e32 v117, 0x80f, v4
	v_add_u32_e32 v4, 33, v107
	v_and_b32_e32 v1, 3, v209
	s_addc_u32 s81, s87, 0
	v_min_i32_e32 v126, 0x80f, v4
	v_cmp_gt_i32_e64 s[26:27], 16, v4
	v_min_u32_e32 v127, 0x80f, v5
	v_min_u32_e32 v131, 0x80f, v4
	v_lshlrev_b32_e32 v4, 6, v122
	v_lshlrev_b32_e32 v5, 4, v1
	s_add_u32 s82, s86, 0x5d40000
	v_add_u32_e32 v135, s0, v134
	v_add3_u32 v137, s0, v4, v5
	v_lshlrev_b32_e32 v4, 2, v1
	v_add_u32_e32 v1, -16, v122
	s_movk_i32 s0, 0xf7ff
	v_lshlrev_b32_e32 v6, 1, v46
	v_mov_b32_e32 v7, v0
	s_addc_u32 s83, s87, 0
	v_cmp_lt_u32_e32 vcc, s0, v1
	v_lshl_add_u64 v[8:9], s[86:87], 0, v[6:7]
	s_mov_b64 s[8:9], 0x7dc0000
	s_add_u32 s92, s86, 0xb700000
	v_min_u32_e32 v115, 0x80f, v107
	v_bfe_u32 v119, v209, 2, 5
	v_lshl_add_u64 v[52:53], v[8:9], 0, s[8:9]
	s_addc_u32 s93, s87, 0
	s_and_b64 s[8:9], s[72:73], vcc
	v_min_i32_e32 v109, 0x80f, v107
	v_cmp_gt_i32_e64 s[2:3], 16, v107
	v_or_b32_e32 v114, 0x4000, v113
	v_or_b32_e32 v116, 0x4000, v115
	v_cmp_lt_i32_e64 s[14:15], -2, v107
	v_or_b32_e32 v118, 0x4000, v117
	v_cmp_gt_u32_e64 s[18:19], 16, v119
	v_mul_i32_i24_e32 v120, 0x650, v107
	v_cmp_eq_u32_e64 s[20:21], 0, v47
	v_mul_i32_i24_e32 v123, 0x650, v122
	v_cmp_gt_i32_e64 s[24:25], -16, v107
	v_or_b32_e32 v128, 0x4000, v127
	v_or_b32_e32 v130, 0x4000, v129
	v_or_b32_e32 v132, 0x4000, v131
	v_or_b32_e32 v133, 32, v119
	v_add_u32_e32 v136, 63, v107
	v_add_u32_e32 v138, 0x7f0, v122
	v_or_b32_e32 v250, 1, v122
	v_and_b32_e32 v251, 1, v122
	v_mul_i32_i24_e32 v250, 0x650, v250
	v_lshl_add_u32 v250, v124, 2, v250
	v_lshl_add_u32 v250, v251, 2, v250
	v_and_b32_e32 v255, 8, v47
	v_cmp_ne_u32_e64 s[42:43], 0, v255
	v_and_b32_e32 v255, 4, v47
	v_cmp_ne_u32_e64 s[44:45], 0, v255
	v_and_b32_e32 v255, 3, v47
	v_cmp_eq_u32_e64 s[46:47], 0, v255
	v_cmp_eq_u32_e64 s[48:49], 1, v255
	v_cmp_eq_u32_e64 s[50:51], 2, v255
	v_cmp_eq_u32_e64 s[52:53], 3, v255
	v_lshlrev_b32_e32 v255, 2, v255
	s_mov_b64 s[98:99], exec
	s_and_b64 exec, s[98:99], s[44:45]
	v_or_b32_e32 v255, 2, v255
	s_and_b64 exec, s[98:99], s[42:43]
	v_or_b32_e32 v255, 1, v255
	s_mov_b64 exec, s[98:99]
	v_lshlrev_b32_e32 v255, 6, v255
	v_cmp_eq_u32_e64 s[54:55], 7, v47
	v_cmp_eq_u32_e64 s[56:57], 8, v47
	v_cmp_eq_u32_e64 s[58:59], 9, v47
	v_cmp_eq_u32_e64 s[60:61], 10, v47
	v_cmp_eq_u32_e64 s[62:63], 11, v47
	v_cmp_eq_u32_e64 s[64:65], 12, v47
	v_cmp_eq_u32_e64 s[66:67], 13, v47
	v_cmp_eq_u32_e64 s[68:69], 14, v47
	v_lshl_add_u64 v[54:55], s[74:75], 0, v[6:7]
	v_lshl_add_u64 v[56:57], s[76:77], 0, v[6:7]
	v_lshl_add_u64 v[58:59], s[78:79], 0, v[6:7]
	v_lshl_add_u64 v[60:61], s[80:81], 0, v[6:7]
	s_and_b64 s[94:95], s[8:9], s[22:23]
	v_add_u32_e32 v49, v3, v124
	v_lshlrev_b32_e32 v62, 1, v2
	v_lshlrev_b32_e32 v64, 1, v4
	v_mov_b32_e32 v139, 0x4000
	v_cmp_eq_u32_e64 s[70:71], 15, v47
	s_branch .LBB0_837

; #define LAS __attribute__((address_space(3)))
; __device__ __forceinline__ float row16_allsum(float x) { x = ROW_ROR_ADD(x, 8); x = ROW_ROR_ADD(x, 4); x = ROW_ROR_ADD(x, 2); x = ROW_ROR_ADD(x, 1); return x; }
; __device__ __forceinline__ f32x4 h4f(u32x2 r) { const h16x4 hv = __builtin_bit_cast(h16x4, r); return (f32x4){(float)hv[0], (float)hv[1], (float)hv[2], (float)hv[3]}; }
; __device__ __forceinline__ f32x4 b4f(u32x2 r) { return (f32x4){__uint_as_float(r.x << 16), __uint_as_float(r.x & 0xffff0000u), __uint_as_float(r.y << 16), __uint_as_float(r.y & 0xffff0000u)}; }
; __device__ __forceinline__ void scan_cvt_write(const Params& P, int h, const ScanRegs& R, LAS unsigned char* buf, int ll) {
;     const int sub = ll & 15, p = ll >> 4;
;     f32x4 f[5][2];
; #pragma unroll
;     for (int i = 0; i < 8; ++i) f[i >> 1][i & 1] = h4f(R.raw[i]);
;     { const f32x4 mu = *(const f32x4*)(P.in[I_MU] + h * 64 + 4 * sub), pm = b4f(R.rr[0]), p0 = b4f(R.rr[1]), p1 = b4f(R.rr[2]); f[4][0] = p0 + (pm - p0) * mu; f[4][1] = p1 + (p0 - p1) * mu; }
; #pragma unroll
;     for (int st = 0; st < 2; ++st) { f[0][st][0] = __expf(-f[0][st][0]); f[0][st][1] = __expf(-f[0][st][1]); f[0][st][2] = __expf(-f[0][st][2]); f[0][st][3] = __expf(-f[0][st][3]); }
;     LAS unsigned char* r0 = buf + (2 * p) * RECB + sub * 16; LAS unsigned char* r1 = r0 + RECB;
; #pragma unroll
;     for (int a = 0; a < 5; ++a) { *(LAS f32x4*)(r0 + a * 256) = f[a][0]; *(LAS f32x4*)(r1 + a * 256) = f[a][1]; }
;     *(LAS f32x4*)(r0 + 1344) = f[0][0] * f[2][1];
;     float be = (f[3][0][0] * f[2][1][0] + f[3][0][1] * f[2][1][1]) + (f[3][0][2] * f[2][1][2] + f[3][0][3] * f[2][1][3]);
;     float ka = (f[1][0][0] * f[2][1][0] + f[1][0][1] * f[2][1][1]) + (f[1][0][2] * f[2][1][2] + f[1][0][3] * f[2][1][3]);
;     be = row16_allsum(be); ka = row16_allsum(ka);
;     if (sub == 0) { typedef float f32x2v __attribute__((ext_vector_type(2))); *(LAS f32x2v*)(buf + (2 * p) * RECB + 1600) = (f32x2v){be, ka}; }
;     if (ll < 128) { const int t = ll >> 2, q = ll & 3; *(LAS f32x4*)(buf + t * RECB + 1280 + q * 16) = h4f(R.rv); }
.LBB0_844:
	s_or_b64 exec, exec, s[8:9]
	v_mov_b32_e32 v1, s30
	v_cndmask_b32_e64 v1, v1, v139, s[18:19]
	v_add_u32_e32 v8, v1, v119
	v_ashrrev_i32_e32 v9, 31, v8
	s_lshl_b32 s0, s37, 6
	v_lshlrev_b64 v[8:9], 10, v[8:9]
	v_lshl_add_u64 v[8:9], s[82:83], 0, v[8:9]
	s_lshl_b32 s8, s0, 1
	s_mov_b32 s9, s1
	v_lshl_add_u64 v[8:9], v[8:9], 0, s[8:9]
	s_lshl_b32 s12, s31, 5
	s_mov_b32 s13, s1
	v_lshl_add_u64 v[8:9], v[8:9], 0, s[12:13]
	v_mov_b32_e32 v63, v0
	s_lshl_b32 s12, s0, 2
	v_lshl_add_u64 v[8:9], v[8:9], 0, v[62:63]
	s_waitcnt vmcnt(0)
	v_cvt_f32_f16_e32 v44, v4
	v_cvt_f32_f16_sdwa v45, v4 dst_sel:DWORD dst_unused:UNUSED_PAD src0_sel:WORD_1
	v_cvt_f32_f16_e32 v63, v5
	v_cvt_f32_f16_sdwa v65, v5 dst_sel:DWORD dst_unused:UNUSED_PAD src0_sel:WORD_1
	v_cvt_f32_f16_sdwa v11, v2 dst_sel:DWORD dst_unused:UNUSED_PAD src0_sel:WORD_1
	v_cvt_f32_f16_e32 v10, v2
	v_cvt_f32_f16_sdwa v13, v3 dst_sel:DWORD dst_unused:UNUSED_PAD src0_sel:WORD_1
	v_cvt_f32_f16_e32 v12, v3
	v_cvt_f32_f16_sdwa v3, v20 dst_sel:DWORD dst_unused:UNUSED_PAD src0_sel:WORD_1
	v_cvt_f32_f16_e32 v2, v20
	v_cvt_f32_f16_sdwa v5, v21 dst_sel:DWORD dst_unused:UNUSED_PAD src0_sel:WORD_1
	v_cvt_f32_f16_e32 v4, v21
	v_lshl_add_u64 v[20:21], v[50:51], 0, s[12:13]
	global_load_dwordx2 v[36:37], v[8:9], off
	v_cvt_f32_f16_e32 v1, v6
	v_cvt_f32_f16_sdwa v29, v6 dst_sel:DWORD dst_unused:UNUSED_PAD src0_sel:WORD_1
	v_cvt_f32_f16_e32 v42, v7
	v_cvt_f32_f16_sdwa v43, v7 dst_sel:DWORD dst_unused:UNUSED_PAD src0_sel:WORD_1
	v_cvt_f32_f16_sdwa v212, v22 dst_sel:DWORD dst_unused:UNUSED_PAD src0_sel:WORD_1
	v_cvt_f32_f16_e32 v210, v22
	v_cvt_f32_f16_sdwa v216, v23 dst_sel:DWORD dst_unused:UNUSED_PAD src0_sel:WORD_1
	v_cvt_f32_f16_e32 v214, v23
	global_load_dwordx4 v[22:25], v[20:21], off
	v_lshlrev_b32_e32 v90, 16, v16
	v_and_b32_e32 v91, 0xffff0000, v16
	v_lshlrev_b32_e32 v20, 16, v17
	v_and_b32_e32 v21, 0xffff0000, v17
	v_lshlrev_b32_e32 v16, 16, v14
	v_and_b32_e32 v17, 0xffff0000, v14
	v_lshlrev_b32_e32 v14, 16, v15
	v_and_b32_e32 v15, 0xffff0000, v15
	v_lshlrev_b32_e32 v40, 16, v19
	v_and_b32_e32 v41, 0xffff0000, v19
	v_sub_f32_e32 v21, v21, v15
	v_sub_f32_e32 v20, v20, v14
	v_mul_f32_e32 v1, 0xbfb8aa3b, v1
	v_lshlrev_b32_e32 v38, 16, v18
	v_and_b32_e32 v39, 0xffff0000, v18
	v_sub_f32_e32 v19, v91, v17
	v_sub_f32_e32 v18, v90, v16
	s_waitcnt vmcnt(0)
	v_pk_fma_f32 v[20:21], v[20:21], v[24:25], v[14:15]
	v_sub_f32_e32 v15, v15, v41
	v_sub_f32_e32 v14, v14, v40
	v_pk_fma_f32 v[24:25], v[24:25], v[14:15], v[40:41]
	v_exp_f32_e32 v14, v1
	v_mul_f32_e32 v1, 0xbfb8aa3b, v29
	v_pk_fma_f32 v[18:19], v[18:19], v[22:23], v[16:17]
	v_sub_f32_e32 v17, v17, v39
	v_sub_f32_e32 v16, v16, v38
	v_exp_f32_e32 v15, v1
	v_mul_f32_e32 v1, 0xbfb8aa3b, v42
	v_pk_fma_f32 v[22:23], v[22:23], v[16:17], v[38:39]
	v_exp_f32_e32 v16, v1
	v_mul_f32_e32 v1, 0xbfb8aa3b, v43
	v_exp_f32_e32 v17, v1
	v_mul_f32_e32 v1, 0xbfb8aa3b, v44
	v_exp_f32_e32 v38, v1
	v_mul_f32_e32 v1, 0xbfb8aa3b, v45
	v_exp_f32_e32 v39, v1
	v_mul_f32_e32 v1, 0xbfb8aa3b, v63
	v_exp_f32_e32 v40, v1
	v_mul_f32_e32 v1, 0xbfb8aa3b, v65
	v_exp_f32_e32 v41, v1
	v_add_u32_e32 v1, v121, v48
	ds_write_b128 v1, v[14:17]
	ds_write_b128 v1, v[38:41] offset:1616
	ds_write_b128 v1, v[10:13] offset:1872
	ds_write_b128 v1, v[2:5] offset:2384
	ds_write_b128 v1, v[18:21] offset:1024
	ds_write_b128 v1, v[22:25] offset:2640
	v_cvt_f32_f16_e32 v7, v30
	v_cvt_f32_f16_sdwa v9, v30 dst_sel:DWORD dst_unused:UNUSED_PAD src0_sel:WORD_1
	v_cvt_f32_f16_e32 v11, v31
	v_cvt_f32_f16_sdwa v13, v31 dst_sel:DWORD dst_unused:UNUSED_PAD src0_sel:WORD_1
	v_cvt_f32_f16_e32 v6, v34
	v_cvt_f32_f16_sdwa v8, v34 dst_sel:DWORD dst_unused:UNUSED_PAD src0_sel:WORD_1
	v_cvt_f32_f16_e32 v10, v35
	v_cvt_f32_f16_sdwa v12, v35 dst_sel:DWORD dst_unused:UNUSED_PAD src0_sel:WORD_1
	v_cvt_f32_f16_e32 v18, v32
	v_cvt_f32_f16_sdwa v20, v32 dst_sel:DWORD dst_unused:UNUSED_PAD src0_sel:WORD_1
	v_cvt_f32_f16_e32 v22, v33
	v_cvt_f32_f16_sdwa v24, v33 dst_sel:DWORD dst_unused:UNUSED_PAD src0_sel:WORD_1
	v_mov_b32_e32 v2, v7
	v_mov_b32_e32 v3, v9
	v_mov_b32_e32 v4, v11
	v_mov_b32_e32 v5, v13
	ds_write_b128 v1, v[2:5] offset:256
	v_mov_b32_e32 v2, v6
	v_mov_b32_e32 v3, v8
	v_mov_b32_e32 v4, v10
	v_mov_b32_e32 v5, v12
	ds_write_b128 v1, v[2:5] offset:2128
	v_mov_b32_e32 v2, v18
	v_mov_b32_e32 v3, v20
	v_mov_b32_e32 v4, v22
	v_mov_b32_e32 v5, v24
	ds_write_b128 v1, v[2:5] offset:768
	v_mov_b32_e32 v2, v10
	v_mov_b32_e32 v3, v12
	v_pk_mul_f32 v[4:5], v[16:17], v[2:3]
	v_mov_b32_e32 v2, v6
	v_mov_b32_e32 v3, v8
	v_mov_b32_e32 v21, v8
	v_mov_b32_e32 v25, v12
	v_pk_mul_f32 v[2:3], v[14:15], v[2:3]
	v_mov_b32_e32 v19, v6
	v_mov_b32_e32 v23, v10
	v_mul_f32_e32 v211, v14, v6
	v_mul_f32_e32 v213, v15, v8
	v_mul_f32_e32 v215, v16, v10
	v_mul_f32_e32 v217, v17, v12
	ds_write_b128 v1, v[210:213] offset:512
	ds_write_b128 v1, v[214:217] offset:1344
	v_pk_mul_f32 v[2:3], v[8:9], v[20:21]
	v_pk_mul_f32 v[4:5], v[12:13], v[24:25]
	v_pk_fma_f32 v[2:3], v[6:7], v[18:19], v[2:3]
	v_pk_fma_f32 v[4:5], v[10:11], v[22:23], v[4:5]
	s_nop 0
	v_pk_add_f32 v[2:3], v[2:3], v[4:5]
	v_mov_b32_e32 v4, v0
	v_mov_b32_e32 v5, v0
	s_nop 0
	v_mov_b32_dpp v4, v2 row_ror:8 row_mask:0xf bank_mask:0xf
	v_mov_b32_dpp v5, v3 row_ror:8 row_mask:0xf bank_mask:0xf
	v_pk_add_f32 v[2:3], v[2:3], v[4:5]
	v_mov_b32_e32 v4, v0
	v_mov_b32_e32 v5, v0
	s_nop 0
	v_mov_b32_dpp v4, v2 row_ror:4 row_mask:0xf bank_mask:0xf
	v_mov_b32_dpp v5, v3 row_ror:4 row_mask:0xf bank_mask:0xf
	v_pk_add_f32 v[2:3], v[2:3], v[4:5]
	v_mov_b32_e32 v4, v0
	v_mov_b32_e32 v5, v0
	s_nop 0
	v_mov_b32_dpp v4, v2 row_ror:2 row_mask:0xf bank_mask:0xf
	v_mov_b32_dpp v5, v3 row_ror:2 row_mask:0xf bank_mask:0xf
	v_pk_add_f32 v[2:3], v[2:3], v[4:5]
	v_mov_b32_e32 v4, v0
	v_mov_b32_e32 v5, v0
	s_nop 0
	v_mov_b32_dpp v4, v2 row_ror:1 row_mask:0xf bank_mask:0xf
	v_mov_b32_dpp v5, v3 row_ror:1 row_mask:0xf bank_mask:0xf
	v_pk_add_f32 v[2:3], v[2:3], v[4:5]
	ds_write_b64 v1, v[2:3] offset:2968
	s_and_saveexec_b64 s[12:13], s[22:23]
	s_cbranch_execz .LBB0_848
	v_cvt_f32_f16_sdwa v3, v36 dst_sel:DWORD dst_unused:UNUSED_PAD src0_sel:WORD_1
	v_cvt_f32_f16_e32 v2, v36
	v_cvt_f32_f16_sdwa v5, v37 dst_sel:DWORD dst_unused:UNUSED_PAD src0_sel:WORD_1
	v_cvt_f32_f16_e32 v4, v37
	ds_write_b32 v250, v2 offset:1344
	ds_write_b32 v250, v3 offset:1360
	ds_write_b32 v250, v4 offset:1376
	ds_write_b32 v250, v5 offset:1392

; #define LAS __attribute__((address_space(3)))
; __device__ __forceinline__ float row16_allsum(float x) { x = ROW_ROR_ADD(x, 8); x = ROW_ROR_ADD(x, 4); x = ROW_ROR_ADD(x, 2); x = ROW_ROR_ADD(x, 1); return x; }
; __device__ __forceinline__ f32x4 h4f(u32x2 r) { const h16x4 hv = __builtin_bit_cast(h16x4, r); return (f32x4){(float)hv[0], (float)hv[1], (float)hv[2], (float)hv[3]}; }
; __device__ __forceinline__ f32x4 b4f(u32x2 r) { return (f32x4){__uint_as_float(r.x << 16), __uint_as_float(r.x & 0xffff0000u), __uint_as_float(r.y << 16), __uint_as_float(r.y & 0xffff0000u)}; }
; __device__ __forceinline__ void scan_cvt_write(const Params& P, int h, const ScanRegs& R, LAS unsigned char* buf, int ll) {
;     const int sub = ll & 15, p = ll >> 4;
;     f32x4 f[5][2];
; #pragma unroll
;     for (int i = 0; i < 8; ++i) f[i >> 1][i & 1] = h4f(R.raw[i]);
;     { const f32x4 mu = *(const f32x4*)(P.in[I_MU] + h * 64 + 4 * sub), pm = b4f(R.rr[0]), p0 = b4f(R.rr[1]), p1 = b4f(R.rr[2]); f[4][0] = p0 + (pm - p0) * mu; f[4][1] = p1 + (p0 - p1) * mu; }
; #pragma unroll
;     for (int st = 0; st < 2; ++st) { f[0][st][0] = __expf(-f[0][st][0]); f[0][st][1] = __expf(-f[0][st][1]); f[0][st][2] = __expf(-f[0][st][2]); f[0][st][3] = __expf(-f[0][st][3]); }
;     LAS unsigned char* r0 = buf + (2 * p) * RECB + sub * 16; LAS unsigned char* r1 = r0 + RECB;
; #pragma unroll
;     for (int a = 0; a < 5; ++a) { *(LAS f32x4*)(r0 + a * 256) = f[a][0]; *(LAS f32x4*)(r1 + a * 256) = f[a][1]; }
;     *(LAS f32x4*)(r0 + 1344) = f[0][0] * f[2][1];
;     float be = (f[3][0][0] * f[2][1][0] + f[3][0][1] * f[2][1][1]) + (f[3][0][2] * f[2][1][2] + f[3][0][3] * f[2][1][3]);
;     float ka = (f[1][0][0] * f[2][1][0] + f[1][0][1] * f[2][1][1]) + (f[1][0][2] * f[2][1][2] + f[1][0][3] * f[2][1][3]);
;     be = row16_allsum(be); ka = row16_allsum(ka);
;     if (sub == 0) { typedef float f32x2v __attribute__((ext_vector_type(2))); *(LAS f32x2v*)(buf + (2 * p) * RECB + 1600) = (f32x2v){be, ka}; }
;     if (ll < 128) { const int t = ll >> 2, q = ll & 3; *(LAS f32x4*)(buf + t * RECB + 1280 + q * 16) = h4f(R.rv); }
.LBB0_860:
	s_cmp_lg_u32 s31, 64
	s_cselect_b64 s[8:9], -1, 0
	s_andn2_b64 vcc, exec, s[72:73]
	s_mov_b64 s[12:13], -1
	s_cbranch_vccnz .LBB0_879
	s_andn2_b64 vcc, exec, s[8:9]
	s_waitcnt lgkmcnt(9)
	v_mov_b64_e32 v[6:7], v[66:67]
	v_mov_b64_e32 v[8:9], v[68:69]
	s_waitcnt lgkmcnt(4)
	v_mov_b64_e32 v[10:11], v[70:71]
	v_mov_b64_e32 v[12:13], v[72:73]
	v_mov_b64_e32 v[14:15], v[74:75]
	v_mov_b64_e32 v[16:17], v[76:77]
	v_mov_b64_e32 v[18:19], v[78:79]
	v_mov_b64_e32 v[20:21], v[80:81]
	v_mov_b64_e32 v[22:23], v[82:83]
	v_mov_b64_e32 v[24:25], v[84:85]
	v_mov_b64_e32 v[26:27], v[86:87]
	v_mov_b64_e32 v[28:29], v[88:89]
	s_cbranch_vccnz .LBB0_873
	global_load_dwordx4 v[6:9], v[90:91], off
	v_cvt_f32_f16_e32 v22, v66
	v_cvt_f32_f16_sdwa v23, v66 dst_sel:DWORD dst_unused:UNUSED_PAD src0_sel:WORD_1
	v_cvt_f32_f16_e32 v24, v67
	v_cvt_f32_f16_sdwa v25, v67 dst_sel:DWORD dst_unused:UNUSED_PAD src0_sel:WORD_1
	s_andn2_b32 s12, 1, s31
	v_cvt_f32_f16_e32 v26, v68
	v_cvt_f32_f16_sdwa v27, v68 dst_sel:DWORD dst_unused:UNUSED_PAD src0_sel:WORD_1
	v_cvt_f32_f16_e32 v28, v69
	v_cvt_f32_f16_sdwa v29, v69 dst_sel:DWORD dst_unused:UNUSED_PAD src0_sel:WORD_1
	v_cvt_f32_f16_sdwa v11, v72 dst_sel:DWORD dst_unused:UNUSED_PAD src0_sel:WORD_1
	v_cvt_f32_f16_e32 v10, v72
	v_cvt_f32_f16_sdwa v13, v73 dst_sel:DWORD dst_unused:UNUSED_PAD src0_sel:WORD_1
	v_cvt_f32_f16_e32 v12, v73
	s_mul_i32 s12, s12, 0xca00
	v_cvt_f32_f16_sdwa v15, v74 dst_sel:DWORD dst_unused:UNUSED_PAD src0_sel:WORD_1
	v_cvt_f32_f16_e32 v14, v74
	v_cvt_f32_f16_sdwa v17, v75 dst_sel:DWORD dst_unused:UNUSED_PAD src0_sel:WORD_1
	v_cvt_f32_f16_e32 v16, v75
	v_lshlrev_b32_e32 v1, 16, v82
	v_lshlrev_b32_e32 v30, 16, v84
	s_add_i32 s36, s12, 0
	v_cvt_f32_f16_sdwa v19, v80 dst_sel:DWORD dst_unused:UNUSED_PAD src0_sel:WORD_1
	v_cvt_f32_f16_e32 v18, v80
	v_cvt_f32_f16_sdwa v21, v81 dst_sel:DWORD dst_unused:UNUSED_PAD src0_sel:WORD_1
	v_cvt_f32_f16_e32 v20, v81
	v_and_b32_e32 v63, 0xffff0000, v82
	v_lshlrev_b32_e32 v65, 16, v83
	s_waitcnt lgkmcnt(2)
	v_and_b32_e32 v106, 0xffff0000, v83
	v_and_b32_e32 v31, 0xffff0000, v84
	v_lshlrev_b32_e32 v32, 16, v85
	v_and_b32_e32 v33, 0xffff0000, v85
	v_sub_f32_e32 v140, v1, v30
	v_add_u32_e32 v1, s36, v120
	v_mul_f32_e32 v22, 0xbfb8aa3b, v22
	v_mul_f32_e32 v23, 0xbfb8aa3b, v23
	v_mul_f32_e32 v24, 0xbfb8aa3b, v24
	v_mul_f32_e32 v25, 0xbfb8aa3b, v25
	v_lshlrev_b32_e32 v34, 16, v86
	v_and_b32_e32 v35, 0xffff0000, v86
	v_lshlrev_b32_e32 v36, 16, v87
	v_and_b32_e32 v37, 0xffff0000, v87
	v_cvt_f32_f16_e32 v39, v70
	v_cvt_f32_f16_sdwa v41, v70 dst_sel:DWORD dst_unused:UNUSED_PAD src0_sel:WORD_1
	v_cvt_f32_f16_e32 v43, v71
	v_cvt_f32_f16_sdwa v45, v71 dst_sel:DWORD dst_unused:UNUSED_PAD src0_sel:WORD_1
	v_sub_f32_e32 v141, v63, v31
	v_sub_f32_e32 v143, v106, v33
	v_sub_f32_e32 v142, v65, v32
	v_mul_f32_e32 v26, 0xbfb8aa3b, v26
	v_mul_f32_e32 v27, 0xbfb8aa3b, v27
	v_mul_f32_e32 v28, 0xbfb8aa3b, v28
	v_mul_f32_e32 v29, 0xbfb8aa3b, v29
	v_add_u32_e32 v63, v1, v48
	v_exp_f32_e32 v22, v22
	v_exp_f32_e32 v23, v23
	v_exp_f32_e32 v24, v24
	v_exp_f32_e32 v25, v25
	v_cvt_f32_f16_e32 v38, v76
	v_cvt_f32_f16_sdwa v40, v76 dst_sel:DWORD dst_unused:UNUSED_PAD src0_sel:WORD_1
	v_cvt_f32_f16_e32 v42, v77
	v_cvt_f32_f16_sdwa v44, v77 dst_sel:DWORD dst_unused:UNUSED_PAD src0_sel:WORD_1
	v_sub_f32_e32 v145, v31, v35
	v_sub_f32_e32 v144, v30, v34
	v_sub_f32_e32 v147, v33, v37
	v_sub_f32_e32 v146, v32, v36
	v_exp_f32_e32 v26, v26
	v_exp_f32_e32 v27, v27
	v_exp_f32_e32 v28, v28
	v_exp_f32_e32 v29, v29
	ds_write_b128 v63, v[10:13] offset:1872
	ds_write_b128 v63, v[18:21] offset:2384
	ds_write_b128 v63, v[22:25]
	ds_write_b128 v63, v[26:29] offset:1616
	s_waitcnt lgkmcnt(6)
	v_cvt_f32_f16_e32 v110, v78
	v_cvt_f32_f16_sdwa v14, v79 dst_sel:DWORD dst_unused:UNUSED_PAD src0_sel:WORD_1
	v_mov_b32_e32 v15, v44
	v_mov_b32_e32 v111, v38
	s_waitcnt vmcnt(0)
	v_pk_fma_f32 v[12:13], v[142:143], v[8:9], v[32:33]
	v_pk_fma_f32 v[10:11], v[140:141], v[6:7], v[30:31]
	v_pk_fma_f32 v[8:9], v[146:147], v[8:9], v[36:37]
	v_pk_fma_f32 v[6:7], v[144:145], v[6:7], v[34:35]
	ds_write_b128 v63, v[10:13] offset:1024
	ds_write_b128 v63, v[6:9] offset:2640
	v_cvt_f32_f16_sdwa v10, v78 dst_sel:DWORD dst_unused:UNUSED_PAD src0_sel:WORD_1
	v_cvt_f32_f16_e32 v12, v79
	v_mov_b32_e32 v6, v39
	v_mov_b32_e32 v7, v41
	v_mov_b32_e32 v8, v43
	v_mov_b32_e32 v9, v45
	ds_write_b128 v63, v[6:9] offset:256
	v_mov_b32_e32 v6, v38
	v_mov_b32_e32 v7, v40
	v_mov_b32_e32 v8, v42
	v_mov_b32_e32 v9, v44
	ds_write_b128 v63, v[6:9] offset:2128
	v_mov_b32_e32 v6, v110
	v_mov_b32_e32 v7, v10
	v_mov_b32_e32 v8, v12
	v_mov_b32_e32 v9, v14
	ds_write_b128 v63, v[6:9] offset:768
	v_mov_b32_e32 v6, v42
	v_mov_b32_e32 v7, v44
	v_pk_mul_f32 v[8:9], v[24:25], v[6:7]
	v_mov_b32_e32 v6, v38
	v_mov_b32_e32 v7, v40
	v_mov_b32_e32 v11, v40
	v_pk_mul_f32 v[6:7], v[22:23], v[6:7]
	v_mov_b32_e32 v13, v42
	v_cvt_f32_f16_e32 v210, v74
	v_mul_f32_e32 v211, v22, v38
	v_cvt_f32_f16_sdwa v212, v74 dst_sel:DWORD dst_unused:UNUSED_PAD src0_sel:WORD_1
	v_mul_f32_e32 v213, v23, v40
	v_cvt_f32_f16_e32 v214, v75
	v_mul_f32_e32 v215, v24, v42
	v_cvt_f32_f16_sdwa v216, v75 dst_sel:DWORD dst_unused:UNUSED_PAD src0_sel:WORD_1
	v_mul_f32_e32 v217, v25, v44
	ds_write_b128 v63, v[210:213] offset:512
	ds_write_b128 v63, v[214:217] offset:1344
	v_pk_mul_f32 v[6:7], v[40:41], v[10:11]
	v_pk_mul_f32 v[8:9], v[44:45], v[14:15]
	v_pk_fma_f32 v[6:7], v[38:39], v[110:111], v[6:7]
	v_pk_fma_f32 v[8:9], v[42:43], v[12:13], v[8:9]
	s_nop 0
	v_pk_add_f32 v[6:7], v[6:7], v[8:9]
	v_mov_b32_e32 v8, v0
	v_mov_b32_e32 v9, v0
	s_nop 0
	v_mov_b32_dpp v8, v6 row_ror:8 row_mask:0xf bank_mask:0xf
	v_mov_b32_dpp v9, v7 row_ror:8 row_mask:0xf bank_mask:0xf
	v_pk_add_f32 v[6:7], v[6:7], v[8:9]
	v_mov_b32_e32 v8, v0
	v_mov_b32_e32 v9, v0
	s_nop 0
	v_mov_b32_dpp v8, v6 row_ror:4 row_mask:0xf bank_mask:0xf
	v_mov_b32_dpp v9, v7 row_ror:4 row_mask:0xf bank_mask:0xf
	v_pk_add_f32 v[6:7], v[6:7], v[8:9]
	v_mov_b32_e32 v8, v0
	v_mov_b32_e32 v9, v0
	s_nop 0
	v_mov_b32_dpp v8, v6 row_ror:2 row_mask:0xf bank_mask:0xf
	v_mov_b32_dpp v9, v7 row_ror:2 row_mask:0xf bank_mask:0xf
	v_pk_add_f32 v[6:7], v[6:7], v[8:9]
	v_mov_b32_e32 v8, v0
	v_mov_b32_e32 v9, v0
	s_nop 0
	v_mov_b32_dpp v8, v6 row_ror:1 row_mask:0xf bank_mask:0xf
	v_mov_b32_dpp v9, v7 row_ror:1 row_mask:0xf bank_mask:0xf
	v_pk_add_f32 v[6:7], v[6:7], v[8:9]
	ds_write_b64 v63, v[6:7] offset:2968
	s_and_saveexec_b64 s[12:13], s[22:23]
	s_cbranch_execz .LBB0_866
	v_cvt_f32_f16_sdwa v7, v88 dst_sel:DWORD dst_unused:UNUSED_PAD src0_sel:WORD_1
	v_cvt_f32_f16_e32 v6, v88
	v_cvt_f32_f16_sdwa v9, v89 dst_sel:DWORD dst_unused:UNUSED_PAD src0_sel:WORD_1
	v_cvt_f32_f16_e32 v8, v89
	v_add_u32_e32 v1, s36, v250
	ds_write_b32 v1, v6 offset:1344
	ds_write_b32 v1, v7 offset:1360
	ds_write_b32 v1, v8 offset:1376
	ds_write_b32 v1, v9 offset:1392

; #define LAS __attribute__((address_space(3)))
; __device__ __forceinline__ float row16_allsum(float x) { x = ROW_ROR_ADD(x, 8); x = ROW_ROR_ADD(x, 4); x = ROW_ROR_ADD(x, 2); x = ROW_ROR_ADD(x, 1); return x; }
; __device__ __forceinline__ float dot4(f32x4 a, f32x4 b) { return __builtin_fmaf(a[3], b[3], __builtin_fmaf(a[2], b[2], __builtin_fmaf(a[1], b[1], a[0] * b[0]))); }
; __device__ __forceinline__ void scan_phase(const Params& P, LAS unsigned char* lds, int tid, int wid, int lane) {
;     ...
;                 const LAS unsigned char* buf = lds + (ck & 1) * SBUF + jq * 16; const LAS unsigned char* vbuf = lds + (ck & 1) * SBUF + 1280 + il * 4; const LAS unsigned char* sbuf = lds + (ck & 1) * SBUF + 1600;
;                 LAS float* yb = (LAS float*)(lds + YOFF + (ck & 1) * 2048);
;                 f32x4 w0[2], kh0[2], kk0[2], b0[2], r0[2], wk0[2], w1[2], kh1[2], b1[2], r1[2]; float v0[2], v1[2]; f32x2v bk[2];
;     ...
;                 SC_LOADP(0, 0);
;                 for (int t0 = 0; t0 < nsteps; t0 += 16) {
;                     float ykeep = 0.f;
; #pragma unroll
;                     for (int u = 0; u < 8; ++u) {
;                         SC_LOADP((u + 1) & 1, t0 + 2 * u + 2);
;                         const int s = u & 1;
;                         float dA = dot4(S, kk0[s]), dB = dot4(S, wk0[s]);
;                         dA = row16_allsum(dA); dB = row16_allsum(dB);
;                         const float sa0 = -dA;
;                         const f32x4 S0 = S * w0[s] + (b0[s] * sa0 + kh0[s] * v0[s]);
;                         const float sa1 = -(dB + sa0 * bk[s].x + v0[s] * bk[s].y);
;                         const f32x4 S1 = S0 * w1[s] + (b1[s] * sa1 + kh1[s] * v1[s]);
;                         float y0 = dot4(S0, r0[s]), y1 = dot4(S1, r1[s]);
.LBB0_879:
	s_andn2_b64 vcc, exec, s[12:13]
	s_cbranch_vccnz .LBB0_858
	s_and_b32 s12, s31, 1
	s_mul_i32 s13, s12, 0xca00
	s_add_i32 s36, s13, 0
	v_add_u32_e32 v1, s36, v48
	s_waitcnt vmcnt(3) lgkmcnt(13)
	ds_read_b128 v[14:17], v1
	s_waitcnt vmcnt(1) lgkmcnt(13)
	ds_read_b128 v[22:25], v1 offset:256
	s_waitcnt lgkmcnt(13)
	ds_read_b128 v[42:45], v1 offset:512
	s_waitcnt lgkmcnt(13)
	ds_read_b128 v[34:37], v1 offset:768
	s_waitcnt lgkmcnt(13)
	ds_read_b128 v[6:9], v1 offset:1024
	s_waitcnt lgkmcnt(13)
	ds_read_b128 v[38:41], v1 offset:1344
	s_waitcnt lgkmcnt(13)
	ds_read_b128 v[18:21], v1 offset:1616
	s_waitcnt vmcnt(0) lgkmcnt(13)
	ds_read_b128 v[26:29], v1 offset:1872
	s_waitcnt lgkmcnt(13)
	ds_read_b128 v[30:33], v1 offset:2384
	s_waitcnt lgkmcnt(13)
	ds_read_b128 v[10:13], v1 offset:2640
	v_lshl_add_u32 v63, v134, 2, s36
	v_mov_b32_e32 v65, s36
	s_waitcnt lgkmcnt(13)
	ds_read_b128 v[108:111], v63 offset:2960
	v_lshl_add_u32 v65, s12, 11, v135
	s_mov_b32 s37, 0
	s_mov_b64 s[12:13], -1
.LBB0_881:
	s_mul_i32 vcc_lo, s37, 0x650
	v_add_u32_e32 v140, vcc_lo, v1
	v_add_u32_e32 v141, vcc_lo, v63
	ds_read_b128 v[152:155], v140 offset:3744
	ds_read_b128 v[164:167], v140 offset:4576
	ds_read_b128 v[148:151], v140 offset:3488
	ds_read_b128 v[184:187], v141 offset:6192
	ds_read_b128 v[172:175], v140 offset:5104
	ds_read_b128 v[156:159], v140 offset:4000
	ds_read_b128 v[144:147], v140 offset:3232
	ds_read_b128 v[176:179], v140 offset:5616
	ds_read_b128 v[168:171], v140 offset:4848
	ds_read_b128 v[160:163], v140 offset:4256
	ds_read_b128 v[180:183], v140 offset:5872
	s_waitcnt lgkmcnt(11)
	v_pk_mul_f32 v[42:43], v[2:3], v[42:43] op_sel_hi:[0,1]
	v_pk_fma_f32 v[42:43], v[2:3], v[44:45], v[42:43] op_sel:[1,0,0] op_sel_hi:[1,1,1]
	v_pk_fma_f32 v[42:43], v[4:5], v[38:39], v[42:43] op_sel:[0,0,0] op_sel_hi:[0,1,1]
	v_pk_fma_f32 v[42:43], v[4:5], v[40:41], v[42:43] op_sel:[1,0,0] op_sel_hi:[1,1,1]
	v_pk_mul_f32 v[190:191], v[22:23], v[108:109] op_sel_hi:[1,0]
	v_pk_mul_f32 v[192:193], v[24:25], v[108:109] op_sel_hi:[1,0]
	v_add_f32_dpp v42, v42, v42 row_ror:8 row_mask:0xf bank_mask:0xf bound_ctrl:1
	v_add_f32_dpp v43, v43, v43 row_ror:8 row_mask:0xf bank_mask:0xf bound_ctrl:1
	v_pk_mul_f32 v[44:45], v[26:27], v[108:109] op_sel:[0,1] op_sel_hi:[1,1]
	v_add_f32_dpp v42, v42, v42 row_ror:4 row_mask:0xf bank_mask:0xf bound_ctrl:1
	v_add_f32_dpp v43, v43, v43 row_ror:4 row_mask:0xf bank_mask:0xf bound_ctrl:1
	v_pk_mul_f32 v[40:41], v[28:29], v[108:109] op_sel:[0,1] op_sel_hi:[1,1]
	v_add_f32_dpp v42, v42, v42 row_ror:2 row_mask:0xf bank_mask:0xf bound_ctrl:1
	v_add_f32_dpp v43, v43, v43 row_ror:2 row_mask:0xf bank_mask:0xf bound_ctrl:1
	s_nop 0
	v_add_f32_dpp v42, v42, v42 row_ror:1 row_mask:0xf bank_mask:0xf bound_ctrl:1
	v_add_f32_dpp v43, v43, v43 row_ror:1 row_mask:0xf bank_mask:0xf bound_ctrl:1
	v_pk_fma_f32 v[190:191], v[34:35], v[42:43], v[190:191] op_sel_hi:[1,0,1] neg_lo:[0,1,0] neg_hi:[0,1,0]
	v_pk_fma_f32 v[192:193], v[36:37], v[42:43], v[192:193] op_sel_hi:[1,0,1] neg_lo:[0,1,0] neg_hi:[0,1,0]
	v_fma_f32 v43, -v42, v110, v43
	v_pk_fma_f32 v[190:191], v[2:3], v[14:15], v[190:191]
	v_pk_fma_f32 v[192:193], v[4:5], v[16:17], v[192:193]
	v_fma_f32 v43, v108, v111, v43
	v_pk_mul_f32 v[6:7], v[190:191], v[6:7]
	v_pk_fma_f32 v[44:45], v[30:31], v[42:43], v[44:45] op_sel:[0,1,0] op_sel_hi:[1,1,1] neg_lo:[0,1,0] neg_hi:[0,1,0]
	v_pk_fma_f32 v[6:7], v[192:193], v[8:9], v[6:7]
	v_pk_fma_f32 v[40:41], v[32:33], v[42:43], v[40:41] op_sel:[0,1,0] op_sel_hi:[1,1,1] neg_lo:[0,1,0] neg_hi:[0,1,0]
	v_add_f32_e32 v194, v6, v7
	v_pk_fma_f32 v[2:3], v[190:191], v[18:19], v[44:45]
	v_pk_fma_f32 v[4:5], v[192:193], v[20:21], v[40:41]
	v_pk_mul_f32 v[10:11], v[2:3], v[10:11]
	v_pk_fma_f32 v[10:11], v[4:5], v[12:13], v[10:11]
	v_add_f32_e32 v195, v10, v11
	ds_read_b128 v[42:45], v140 offset:6976
	ds_read_b128 v[38:41], v140 offset:7808
	ds_read_b128 v[22:25], v140 offset:6720
	ds_read_b128 v[108:111], v141 offset:9424
	ds_read_b128 v[26:29], v140 offset:8336
	ds_read_b128 v[34:37], v140 offset:7232
	ds_read_b128 v[14:17], v140 offset:6464
	ds_read_b128 v[30:33], v140 offset:8848
	ds_read_b128 v[18:21], v140 offset:8080
	ds_read_b128 v[6:9], v140 offset:7488
	ds_read_b128 v[10:13], v140 offset:9104
	s_waitcnt lgkmcnt(11)
; __device__ __forceinline__ float row16_allsum(float x) { x = ROW_ROR_ADD(x, 8); x = ROW_ROR_ADD(x, 4); x = ROW_ROR_ADD(x, 2); x = ROW_ROR_ADD(x, 1); return x; }
; __device__ __forceinline__ float dot4(f32x4 a, f32x4 b) { return __builtin_fmaf(a[3], b[3], __builtin_fmaf(a[2], b[2], __builtin_fmaf(a[1], b[1], a[0] * b[0]))); }
; __device__ __forceinline__ void scan_phase(const Params& P, LAS unsigned char* lds, int tid, int wid, int lane) {
;     ...
;                 for (int t0 = 0; t0 < nsteps; t0 += 16) {
;                     float ykeep = 0.f;
; #pragma unroll
;                     for (int u = 0; u < 8; ++u) {
;                         SC_LOADP((u + 1) & 1, t0 + 2 * u + 2);
;                         const int s = u & 1;
;                         float dA = dot4(S, kk0[s]), dB = dot4(S, wk0[s]);
;                         dA = row16_allsum(dA); dB = row16_allsum(dB);
;                         const float sa0 = -dA;
;                         const f32x4 S0 = S * w0[s] + (b0[s] * sa0 + kh0[s] * v0[s]);
;                         const float sa1 = -(dB + sa0 * bk[s].x + v0[s] * bk[s].y);
;                         const f32x4 S1 = S0 * w1[s] + (b1[s] * sa1 + kh1[s] * v1[s]);
;                         float y0 = dot4(S0, r0[s]), y1 = dot4(S1, r1[s]);
;                         y0 = row16_allsum(y0); y1 = row16_allsum(y1);
;                         ykeep = (jq == 2 * u) ? y0 : ykeep; ykeep = (jq == 2 * u + 1) ? y1 : ykeep;
;                         S = S1;
;                     }
;                     yb[(t0 + jq) * 16 + il] = ykeep;
	v_pk_mul_f32 v[152:153], v[2:3], v[152:153] op_sel_hi:[0,1]
	v_pk_fma_f32 v[152:153], v[2:3], v[154:155], v[152:153] op_sel:[1,0,0] op_sel_hi:[1,1,1]
	v_pk_fma_f32 v[152:153], v[4:5], v[164:165], v[152:153] op_sel:[0,0,0] op_sel_hi:[0,1,1]
	v_pk_fma_f32 v[152:153], v[4:5], v[166:167], v[152:153] op_sel:[1,0,0] op_sel_hi:[1,1,1]
	v_pk_mul_f32 v[190:191], v[148:149], v[184:185] op_sel_hi:[1,0]
	v_pk_mul_f32 v[192:193], v[150:151], v[184:185] op_sel_hi:[1,0]
	v_add_f32_dpp v152, v152, v152 row_ror:8 row_mask:0xf bank_mask:0xf bound_ctrl:1
	v_add_f32_dpp v153, v153, v153 row_ror:8 row_mask:0xf bank_mask:0xf bound_ctrl:1
	v_pk_mul_f32 v[154:155], v[172:173], v[184:185] op_sel:[0,1] op_sel_hi:[1,1]
	v_add_f32_dpp v152, v152, v152 row_ror:4 row_mask:0xf bank_mask:0xf bound_ctrl:1
	v_add_f32_dpp v153, v153, v153 row_ror:4 row_mask:0xf bank_mask:0xf bound_ctrl:1
	v_pk_mul_f32 v[166:167], v[174:175], v[184:185] op_sel:[0,1] op_sel_hi:[1,1]
	v_add_f32_dpp v152, v152, v152 row_ror:2 row_mask:0xf bank_mask:0xf bound_ctrl:1
	v_add_f32_dpp v153, v153, v153 row_ror:2 row_mask:0xf bank_mask:0xf bound_ctrl:1
	s_nop 0
	v_add_f32_dpp v152, v152, v152 row_ror:1 row_mask:0xf bank_mask:0xf bound_ctrl:1
	v_add_f32_dpp v153, v153, v153 row_ror:1 row_mask:0xf bank_mask:0xf bound_ctrl:1
	v_pk_fma_f32 v[190:191], v[156:157], v[152:153], v[190:191] op_sel_hi:[1,0,1] neg_lo:[0,1,0] neg_hi:[0,1,0]
	v_pk_fma_f32 v[192:193], v[158:159], v[152:153], v[192:193] op_sel_hi:[1,0,1] neg_lo:[0,1,0] neg_hi:[0,1,0]
	v_fma_f32 v153, -v152, v186, v153
	v_pk_fma_f32 v[190:191], v[2:3], v[144:145], v[190:191]
	v_pk_fma_f32 v[192:193], v[4:5], v[146:147], v[192:193]
	v_fma_f32 v153, v184, v187, v153
	v_pk_mul_f32 v[160:161], v[190:191], v[160:161]
	v_pk_fma_f32 v[154:155], v[176:177], v[152:153], v[154:155] op_sel:[0,1,0] op_sel_hi:[1,1,1] neg_lo:[0,1,0] neg_hi:[0,1,0]
	v_pk_fma_f32 v[160:161], v[192:193], v[162:163], v[160:161]
	v_pk_fma_f32 v[166:167], v[178:179], v[152:153], v[166:167] op_sel:[0,1,0] op_sel_hi:[1,1,1] neg_lo:[0,1,0] neg_hi:[0,1,0]
	v_add_f32_e32 v196, v160, v161
	v_pk_fma_f32 v[2:3], v[190:191], v[168:169], v[154:155]
	v_pk_fma_f32 v[4:5], v[192:193], v[170:171], v[166:167]
	v_pk_mul_f32 v[180:181], v[2:3], v[180:181]
	v_pk_fma_f32 v[180:181], v[4:5], v[182:183], v[180:181]
	v_add_f32_e32 v197, v180, v181
	v_add_f32_dpp v194, v194, v194 row_ror:8 row_mask:0xf bank_mask:0xf bound_ctrl:1
	v_add_f32_dpp v195, v195, v195 row_ror:8 row_mask:0xf bank_mask:0xf bound_ctrl:1
	v_add_f32_dpp v196, v196, v196 row_ror:8 row_mask:0xf bank_mask:0xf bound_ctrl:1
	v_add_f32_dpp v197, v197, v197 row_ror:8 row_mask:0xf bank_mask:0xf bound_ctrl:1
	v_cndmask_b32_e64 v194, v194, v195, s[42:43]
	v_cndmask_b32_e64 v196, v196, v197, s[42:43]
	ds_read_b128 v[152:155], v140 offset:10208
	ds_read_b128 v[164:167], v140 offset:11040
	ds_read_b128 v[148:151], v140 offset:9952
	ds_read_b128 v[184:187], v141 offset:12656
	ds_read_b128 v[172:175], v140 offset:11568
	ds_read_b128 v[156:159], v140 offset:10464
	ds_read_b128 v[144:147], v140 offset:9696
	ds_read_b128 v[176:179], v140 offset:12080
	ds_read_b128 v[168:171], v140 offset:11312
	ds_read_b128 v[160:163], v140 offset:10720
	ds_read_b128 v[180:183], v140 offset:12336
	v_add_f32_dpp v194, v194, v194 row_half_mirror row_mask:0xf bank_mask:0xf bound_ctrl:1
	v_add_f32_dpp v196, v196, v196 row_half_mirror row_mask:0xf bank_mask:0xf bound_ctrl:1
	s_waitcnt lgkmcnt(11)
	v_cndmask_b32_e64 v194, v194, v196, s[44:45]
	v_pk_mul_f32 v[42:43], v[2:3], v[42:43] op_sel_hi:[0,1]
	v_pk_fma_f32 v[42:43], v[2:3], v[44:45], v[42:43] op_sel:[1,0,0] op_sel_hi:[1,1,1]
	v_add_f32_dpp v194, v194, v194 quad_perm:[1,0,3,2] row_mask:0xf bank_mask:0xf bound_ctrl:1
	v_pk_fma_f32 v[42:43], v[4:5], v[38:39], v[42:43] op_sel:[0,0,0] op_sel_hi:[0,1,1]
	v_pk_fma_f32 v[42:43], v[4:5], v[40:41], v[42:43] op_sel:[1,0,0] op_sel_hi:[1,1,1]
	v_add_f32_dpp v194, v194, v194 quad_perm:[2,3,0,1] row_mask:0xf bank_mask:0xf bound_ctrl:1
	v_pk_mul_f32 v[190:191], v[22:23], v[108:109] op_sel_hi:[1,0]
	v_pk_mul_f32 v[192:193], v[24:25], v[108:109] op_sel_hi:[1,0]
	v_cndmask_b32_e64 v143, v143, v194, s[46:47]
	v_add_f32_dpp v42, v42, v42 row_ror:8 row_mask:0xf bank_mask:0xf bound_ctrl:1
	v_add_f32_dpp v43, v43, v43 row_ror:8 row_mask:0xf bank_mask:0xf bound_ctrl:1
	v_pk_mul_f32 v[44:45], v[26:27], v[108:109] op_sel:[0,1] op_sel_hi:[1,1]
	v_add_f32_dpp v42, v42, v42 row_ror:4 row_mask:0xf bank_mask:0xf bound_ctrl:1
	v_add_f32_dpp v43, v43, v43 row_ror:4 row_mask:0xf bank_mask:0xf bound_ctrl:1
	v_pk_mul_f32 v[40:41], v[28:29], v[108:109] op_sel:[0,1] op_sel_hi:[1,1]
	v_add_f32_dpp v42, v42, v42 row_ror:2 row_mask:0xf bank_mask:0xf bound_ctrl:1
	v_add_f32_dpp v43, v43, v43 row_ror:2 row_mask:0xf bank_mask:0xf bound_ctrl:1
	s_nop 0
	v_add_f32_dpp v42, v42, v42 row_ror:1 row_mask:0xf bank_mask:0xf bound_ctrl:1
	v_add_f32_dpp v43, v43, v43 row_ror:1 row_mask:0xf bank_mask:0xf bound_ctrl:1
	v_pk_fma_f32 v[190:191], v[34:35], v[42:43], v[190:191] op_sel_hi:[1,0,1] neg_lo:[0,1,0] neg_hi:[0,1,0]
	v_pk_fma_f32 v[192:193], v[36:37], v[42:43], v[192:193] op_sel_hi:[1,0,1] neg_lo:[0,1,0] neg_hi:[0,1,0]
	v_fma_f32 v43, -v42, v110, v43
	v_pk_fma_f32 v[190:191], v[2:3], v[14:15], v[190:191]
	v_pk_fma_f32 v[192:193], v[4:5], v[16:17], v[192:193]
	v_fma_f32 v43, v108, v111, v43
	v_pk_mul_f32 v[6:7], v[190:191], v[6:7]
	v_pk_fma_f32 v[44:45], v[30:31], v[42:43], v[44:45] op_sel:[0,1,0] op_sel_hi:[1,1,1] neg_lo:[0,1,0] neg_hi:[0,1,0]
	v_pk_fma_f32 v[6:7], v[192:193], v[8:9], v[6:7]
	v_pk_fma_f32 v[40:41], v[32:33], v[42:43], v[40:41] op_sel:[0,1,0] op_sel_hi:[1,1,1] neg_lo:[0,1,0] neg_hi:[0,1,0]
	v_add_f32_e32 v194, v6, v7
	v_pk_fma_f32 v[2:3], v[190:191], v[18:19], v[44:45]
	v_pk_fma_f32 v[4:5], v[192:193], v[20:21], v[40:41]
	v_pk_mul_f32 v[10:11], v[2:3], v[10:11]
	v_pk_fma_f32 v[10:11], v[4:5], v[12:13], v[10:11]
	v_add_f32_e32 v195, v10, v11
	ds_read_b128 v[42:45], v140 offset:13440
	ds_read_b128 v[38:41], v140 offset:14272
	ds_read_b128 v[22:25], v140 offset:13184
	ds_read_b128 v[108:111], v141 offset:15888
	ds_read_b128 v[26:29], v140 offset:14800
	ds_read_b128 v[34:37], v140 offset:13696
	ds_read_b128 v[14:17], v140 offset:12928
	ds_read_b128 v[30:33], v140 offset:15312
	ds_read_b128 v[18:21], v140 offset:14544
	ds_read_b128 v[6:9], v140 offset:13952
	ds_read_b128 v[10:13], v140 offset:15568
	s_waitcnt lgkmcnt(11)
; __device__ __forceinline__ float row16_allsum(float x) { x = ROW_ROR_ADD(x, 8); x = ROW_ROR_ADD(x, 4); x = ROW_ROR_ADD(x, 2); x = ROW_ROR_ADD(x, 1); return x; }
; __device__ __forceinline__ float dot4(f32x4 a, f32x4 b) { return __builtin_fmaf(a[3], b[3], __builtin_fmaf(a[2], b[2], __builtin_fmaf(a[1], b[1], a[0] * b[0]))); }
; __device__ __forceinline__ void scan_phase(const Params& P, LAS unsigned char* lds, int tid, int wid, int lane) {
;     ...
;                 SC_LOADP(0, 0);
;                 for (int t0 = 0; t0 < nsteps; t0 += 16) {
;                     float ykeep = 0.f;
; #pragma unroll
;                     for (int u = 0; u < 8; ++u) {
;                         SC_LOADP((u + 1) & 1, t0 + 2 * u + 2);
;                         const int s = u & 1;
;                         float dA = dot4(S, kk0[s]), dB = dot4(S, wk0[s]);
;                         dA = row16_allsum(dA); dB = row16_allsum(dB);
;                         const float sa0 = -dA;
;                         const f32x4 S0 = S * w0[s] + (b0[s] * sa0 + kh0[s] * v0[s]);
;                         const float sa1 = -(dB + sa0 * bk[s].x + v0[s] * bk[s].y);
;                         const f32x4 S1 = S0 * w1[s] + (b1[s] * sa1 + kh1[s] * v1[s]);
;                         float y0 = dot4(S0, r0[s]), y1 = dot4(S1, r1[s]);
;                         y0 = row16_allsum(y0); y1 = row16_allsum(y1);
;                         ykeep = (jq == 2 * u) ? y0 : ykeep; ykeep = (jq == 2 * u + 1) ? y1 : ykeep;
;                         S = S1;
;                     }
	v_pk_mul_f32 v[152:153], v[2:3], v[152:153] op_sel_hi:[0,1]
	v_pk_fma_f32 v[152:153], v[2:3], v[154:155], v[152:153] op_sel:[1,0,0] op_sel_hi:[1,1,1]
	v_pk_fma_f32 v[152:153], v[4:5], v[164:165], v[152:153] op_sel:[0,0,0] op_sel_hi:[0,1,1]
	v_pk_fma_f32 v[152:153], v[4:5], v[166:167], v[152:153] op_sel:[1,0,0] op_sel_hi:[1,1,1]
	v_pk_mul_f32 v[190:191], v[148:149], v[184:185] op_sel_hi:[1,0]
	v_pk_mul_f32 v[192:193], v[150:151], v[184:185] op_sel_hi:[1,0]
	v_add_f32_dpp v152, v152, v152 row_ror:8 row_mask:0xf bank_mask:0xf bound_ctrl:1
	v_add_f32_dpp v153, v153, v153 row_ror:8 row_mask:0xf bank_mask:0xf bound_ctrl:1
	v_pk_mul_f32 v[154:155], v[172:173], v[184:185] op_sel:[0,1] op_sel_hi:[1,1]
	v_add_f32_dpp v152, v152, v152 row_ror:4 row_mask:0xf bank_mask:0xf bound_ctrl:1
	v_add_f32_dpp v153, v153, v153 row_ror:4 row_mask:0xf bank_mask:0xf bound_ctrl:1
	v_pk_mul_f32 v[166:167], v[174:175], v[184:185] op_sel:[0,1] op_sel_hi:[1,1]
	v_add_f32_dpp v152, v152, v152 row_ror:2 row_mask:0xf bank_mask:0xf bound_ctrl:1
	v_add_f32_dpp v153, v153, v153 row_ror:2 row_mask:0xf bank_mask:0xf bound_ctrl:1
	s_nop 0
	v_add_f32_dpp v152, v152, v152 row_ror:1 row_mask:0xf bank_mask:0xf bound_ctrl:1
	v_add_f32_dpp v153, v153, v153 row_ror:1 row_mask:0xf bank_mask:0xf bound_ctrl:1
	v_pk_fma_f32 v[190:191], v[156:157], v[152:153], v[190:191] op_sel_hi:[1,0,1] neg_lo:[0,1,0] neg_hi:[0,1,0]
	v_pk_fma_f32 v[192:193], v[158:159], v[152:153], v[192:193] op_sel_hi:[1,0,1] neg_lo:[0,1,0] neg_hi:[0,1,0]
	v_fma_f32 v153, -v152, v186, v153
	v_pk_fma_f32 v[190:191], v[2:3], v[144:145], v[190:191]
	v_pk_fma_f32 v[192:193], v[4:5], v[146:147], v[192:193]
	v_fma_f32 v153, v184, v187, v153
	v_pk_mul_f32 v[160:161], v[190:191], v[160:161]
	v_pk_fma_f32 v[154:155], v[176:177], v[152:153], v[154:155] op_sel:[0,1,0] op_sel_hi:[1,1,1] neg_lo:[0,1,0] neg_hi:[0,1,0]
	v_pk_fma_f32 v[160:161], v[192:193], v[162:163], v[160:161]
	v_pk_fma_f32 v[166:167], v[178:179], v[152:153], v[166:167] op_sel:[0,1,0] op_sel_hi:[1,1,1] neg_lo:[0,1,0] neg_hi:[0,1,0]
	v_add_f32_e32 v196, v160, v161
	v_pk_fma_f32 v[2:3], v[190:191], v[168:169], v[154:155]
	v_pk_fma_f32 v[4:5], v[192:193], v[170:171], v[166:167]
	v_pk_mul_f32 v[180:181], v[2:3], v[180:181]
	v_pk_fma_f32 v[180:181], v[4:5], v[182:183], v[180:181]
	v_add_f32_e32 v197, v180, v181
	v_add_f32_dpp v194, v194, v194 row_ror:8 row_mask:0xf bank_mask:0xf bound_ctrl:1
	v_add_f32_dpp v195, v195, v195 row_ror:8 row_mask:0xf bank_mask:0xf bound_ctrl:1
	v_add_f32_dpp v196, v196, v196 row_ror:8 row_mask:0xf bank_mask:0xf bound_ctrl:1
	v_add_f32_dpp v197, v197, v197 row_ror:8 row_mask:0xf bank_mask:0xf bound_ctrl:1
	v_cndmask_b32_e64 v194, v194, v195, s[42:43]
	v_cndmask_b32_e64 v196, v196, v197, s[42:43]
	ds_read_b128 v[152:155], v140 offset:16672
	ds_read_b128 v[164:167], v140 offset:17504
	ds_read_b128 v[148:151], v140 offset:16416
	ds_read_b128 v[184:187], v141 offset:19120
	ds_read_b128 v[172:175], v140 offset:18032
	ds_read_b128 v[156:159], v140 offset:16928
	ds_read_b128 v[144:147], v140 offset:16160
	ds_read_b128 v[176:179], v140 offset:18544
	ds_read_b128 v[168:171], v140 offset:17776
	ds_read_b128 v[160:163], v140 offset:17184
	ds_read_b128 v[180:183], v140 offset:18800
	v_add_f32_dpp v194, v194, v194 row_half_mirror row_mask:0xf bank_mask:0xf bound_ctrl:1
	v_add_f32_dpp v196, v196, v196 row_half_mirror row_mask:0xf bank_mask:0xf bound_ctrl:1
	s_waitcnt lgkmcnt(11)
	v_cndmask_b32_e64 v194, v194, v196, s[44:45]
	v_pk_mul_f32 v[42:43], v[2:3], v[42:43] op_sel_hi:[0,1]
	v_pk_fma_f32 v[42:43], v[2:3], v[44:45], v[42:43] op_sel:[1,0,0] op_sel_hi:[1,1,1]
	v_add_f32_dpp v194, v194, v194 quad_perm:[1,0,3,2] row_mask:0xf bank_mask:0xf bound_ctrl:1
	v_pk_fma_f32 v[42:43], v[4:5], v[38:39], v[42:43] op_sel:[0,0,0] op_sel_hi:[0,1,1]
	v_pk_fma_f32 v[42:43], v[4:5], v[40:41], v[42:43] op_sel:[1,0,0] op_sel_hi:[1,1,1]
	v_add_f32_dpp v194, v194, v194 quad_perm:[2,3,0,1] row_mask:0xf bank_mask:0xf bound_ctrl:1
	v_pk_mul_f32 v[190:191], v[22:23], v[108:109] op_sel_hi:[1,0]
	v_pk_mul_f32 v[192:193], v[24:25], v[108:109] op_sel_hi:[1,0]
	v_cndmask_b32_e64 v143, v143, v194, s[48:49]
	v_add_f32_dpp v42, v42, v42 row_ror:8 row_mask:0xf bank_mask:0xf bound_ctrl:1
	v_add_f32_dpp v43, v43, v43 row_ror:8 row_mask:0xf bank_mask:0xf bound_ctrl:1
	v_pk_mul_f32 v[44:45], v[26:27], v[108:109] op_sel:[0,1] op_sel_hi:[1,1]
	v_add_f32_dpp v42, v42, v42 row_ror:4 row_mask:0xf bank_mask:0xf bound_ctrl:1
	v_add_f32_dpp v43, v43, v43 row_ror:4 row_mask:0xf bank_mask:0xf bound_ctrl:1
	v_pk_mul_f32 v[40:41], v[28:29], v[108:109] op_sel:[0,1] op_sel_hi:[1,1]
	v_add_f32_dpp v42, v42, v42 row_ror:2 row_mask:0xf bank_mask:0xf bound_ctrl:1
	v_add_f32_dpp v43, v43, v43 row_ror:2 row_mask:0xf bank_mask:0xf bound_ctrl:1
	s_nop 0
	v_add_f32_dpp v42, v42, v42 row_ror:1 row_mask:0xf bank_mask:0xf bound_ctrl:1
	v_add_f32_dpp v43, v43, v43 row_ror:1 row_mask:0xf bank_mask:0xf bound_ctrl:1
	v_pk_fma_f32 v[190:191], v[34:35], v[42:43], v[190:191] op_sel_hi:[1,0,1] neg_lo:[0,1,0] neg_hi:[0,1,0]
	v_pk_fma_f32 v[192:193], v[36:37], v[42:43], v[192:193] op_sel_hi:[1,0,1] neg_lo:[0,1,0] neg_hi:[0,1,0]
	v_fma_f32 v43, -v42, v110, v43
	v_pk_fma_f32 v[190:191], v[2:3], v[14:15], v[190:191]
	v_pk_fma_f32 v[192:193], v[4:5], v[16:17], v[192:193]
	v_fma_f32 v43, v108, v111, v43
	v_pk_mul_f32 v[6:7], v[190:191], v[6:7]
	v_pk_fma_f32 v[44:45], v[30:31], v[42:43], v[44:45] op_sel:[0,1,0] op_sel_hi:[1,1,1] neg_lo:[0,1,0] neg_hi:[0,1,0]
	v_pk_fma_f32 v[6:7], v[192:193], v[8:9], v[6:7]
	v_pk_fma_f32 v[40:41], v[32:33], v[42:43], v[40:41] op_sel:[0,1,0] op_sel_hi:[1,1,1] neg_lo:[0,1,0] neg_hi:[0,1,0]
	v_add_f32_e32 v194, v6, v7
	v_pk_fma_f32 v[2:3], v[190:191], v[18:19], v[44:45]
	v_pk_fma_f32 v[4:5], v[192:193], v[20:21], v[40:41]
	v_pk_mul_f32 v[10:11], v[2:3], v[10:11]
	v_pk_fma_f32 v[10:11], v[4:5], v[12:13], v[10:11]
	v_add_f32_e32 v195, v10, v11
	ds_read_b128 v[42:45], v140 offset:19904
	ds_read_b128 v[38:41], v140 offset:20736
	ds_read_b128 v[22:25], v140 offset:19648
	ds_read_b128 v[108:111], v141 offset:22352
	ds_read_b128 v[26:29], v140 offset:21264
	ds_read_b128 v[34:37], v140 offset:20160
	ds_read_b128 v[14:17], v140 offset:19392
	ds_read_b128 v[30:33], v140 offset:21776
	ds_read_b128 v[18:21], v140 offset:21008
	ds_read_b128 v[6:9], v140 offset:20416
	ds_read_b128 v[10:13], v140 offset:22032
	s_waitcnt lgkmcnt(11)
; __device__ __forceinline__ float row16_allsum(float x) { x = ROW_ROR_ADD(x, 8); x = ROW_ROR_ADD(x, 4); x = ROW_ROR_ADD(x, 2); x = ROW_ROR_ADD(x, 1); return x; }
; __device__ __forceinline__ float dot4(f32x4 a, f32x4 b) { return __builtin_fmaf(a[3], b[3], __builtin_fmaf(a[2], b[2], __builtin_fmaf(a[1], b[1], a[0] * b[0]))); }
; __device__ __forceinline__ void scan_phase(const Params& P, LAS unsigned char* lds, int tid, int wid, int lane) {
;     ...
;                 SC_LOADP(0, 0);
;                 for (int t0 = 0; t0 < nsteps; t0 += 16) {
;                     float ykeep = 0.f;
; #pragma unroll
;                     for (int u = 0; u < 8; ++u) {
;                         SC_LOADP((u + 1) & 1, t0 + 2 * u + 2);
;                         const int s = u & 1;
;                         float dA = dot4(S, kk0[s]), dB = dot4(S, wk0[s]);
;                         dA = row16_allsum(dA); dB = row16_allsum(dB);
;                         const float sa0 = -dA;
;                         const f32x4 S0 = S * w0[s] + (b0[s] * sa0 + kh0[s] * v0[s]);
;                         const float sa1 = -(dB + sa0 * bk[s].x + v0[s] * bk[s].y);
;                         const f32x4 S1 = S0 * w1[s] + (b1[s] * sa1 + kh1[s] * v1[s]);
;                         float y0 = dot4(S0, r0[s]), y1 = dot4(S1, r1[s]);
;                         y0 = row16_allsum(y0); y1 = row16_allsum(y1);
;                         ykeep = (jq == 2 * u) ? y0 : ykeep; ykeep = (jq == 2 * u + 1) ? y1 : ykeep;
;                         S = S1;
;                     }
	v_pk_mul_f32 v[152:153], v[2:3], v[152:153] op_sel_hi:[0,1]
	v_pk_fma_f32 v[152:153], v[2:3], v[154:155], v[152:153] op_sel:[1,0,0] op_sel_hi:[1,1,1]
	v_pk_fma_f32 v[152:153], v[4:5], v[164:165], v[152:153] op_sel:[0,0,0] op_sel_hi:[0,1,1]
	v_pk_fma_f32 v[152:153], v[4:5], v[166:167], v[152:153] op_sel:[1,0,0] op_sel_hi:[1,1,1]
	v_pk_mul_f32 v[190:191], v[148:149], v[184:185] op_sel_hi:[1,0]
	v_pk_mul_f32 v[192:193], v[150:151], v[184:185] op_sel_hi:[1,0]
	v_add_f32_dpp v152, v152, v152 row_ror:8 row_mask:0xf bank_mask:0xf bound_ctrl:1
	v_add_f32_dpp v153, v153, v153 row_ror:8 row_mask:0xf bank_mask:0xf bound_ctrl:1
	v_pk_mul_f32 v[154:155], v[172:173], v[184:185] op_sel:[0,1] op_sel_hi:[1,1]
	v_add_f32_dpp v152, v152, v152 row_ror:4 row_mask:0xf bank_mask:0xf bound_ctrl:1
	v_add_f32_dpp v153, v153, v153 row_ror:4 row_mask:0xf bank_mask:0xf bound_ctrl:1
	v_pk_mul_f32 v[166:167], v[174:175], v[184:185] op_sel:[0,1] op_sel_hi:[1,1]
	v_add_f32_dpp v152, v152, v152 row_ror:2 row_mask:0xf bank_mask:0xf bound_ctrl:1
	v_add_f32_dpp v153, v153, v153 row_ror:2 row_mask:0xf bank_mask:0xf bound_ctrl:1
	s_nop 0
	v_add_f32_dpp v152, v152, v152 row_ror:1 row_mask:0xf bank_mask:0xf bound_ctrl:1
	v_add_f32_dpp v153, v153, v153 row_ror:1 row_mask:0xf bank_mask:0xf bound_ctrl:1
	v_pk_fma_f32 v[190:191], v[156:157], v[152:153], v[190:191] op_sel_hi:[1,0,1] neg_lo:[0,1,0] neg_hi:[0,1,0]
	v_pk_fma_f32 v[192:193], v[158:159], v[152:153], v[192:193] op_sel_hi:[1,0,1] neg_lo:[0,1,0] neg_hi:[0,1,0]
	v_fma_f32 v153, -v152, v186, v153
	v_pk_fma_f32 v[190:191], v[2:3], v[144:145], v[190:191]
	v_pk_fma_f32 v[192:193], v[4:5], v[146:147], v[192:193]
	v_fma_f32 v153, v184, v187, v153
	v_pk_mul_f32 v[160:161], v[190:191], v[160:161]
	v_pk_fma_f32 v[154:155], v[176:177], v[152:153], v[154:155] op_sel:[0,1,0] op_sel_hi:[1,1,1] neg_lo:[0,1,0] neg_hi:[0,1,0]
	v_pk_fma_f32 v[160:161], v[192:193], v[162:163], v[160:161]
	v_pk_fma_f32 v[166:167], v[178:179], v[152:153], v[166:167] op_sel:[0,1,0] op_sel_hi:[1,1,1] neg_lo:[0,1,0] neg_hi:[0,1,0]
	v_add_f32_e32 v196, v160, v161
	v_pk_fma_f32 v[2:3], v[190:191], v[168:169], v[154:155]
	v_pk_fma_f32 v[4:5], v[192:193], v[170:171], v[166:167]
	v_pk_mul_f32 v[180:181], v[2:3], v[180:181]
	v_pk_fma_f32 v[180:181], v[4:5], v[182:183], v[180:181]
	v_add_f32_e32 v197, v180, v181
	v_add_f32_dpp v194, v194, v194 row_ror:8 row_mask:0xf bank_mask:0xf bound_ctrl:1
	v_add_f32_dpp v195, v195, v195 row_ror:8 row_mask:0xf bank_mask:0xf bound_ctrl:1
	v_add_f32_dpp v196, v196, v196 row_ror:8 row_mask:0xf bank_mask:0xf bound_ctrl:1
	v_add_f32_dpp v197, v197, v197 row_ror:8 row_mask:0xf bank_mask:0xf bound_ctrl:1
	v_cndmask_b32_e64 v194, v194, v195, s[42:43]
	v_cndmask_b32_e64 v196, v196, v197, s[42:43]
	ds_read_b128 v[152:155], v140 offset:23136
	ds_read_b128 v[164:167], v140 offset:23968
	ds_read_b128 v[148:151], v140 offset:22880
	ds_read_b128 v[184:187], v141 offset:25584
	ds_read_b128 v[172:175], v140 offset:24496
	ds_read_b128 v[156:159], v140 offset:23392
	ds_read_b128 v[144:147], v140 offset:22624
	ds_read_b128 v[176:179], v140 offset:25008
	ds_read_b128 v[168:171], v140 offset:24240
	ds_read_b128 v[160:163], v140 offset:23648
	ds_read_b128 v[180:183], v140 offset:25264
	v_add_f32_dpp v194, v194, v194 row_half_mirror row_mask:0xf bank_mask:0xf bound_ctrl:1
	v_add_f32_dpp v196, v196, v196 row_half_mirror row_mask:0xf bank_mask:0xf bound_ctrl:1
	s_waitcnt lgkmcnt(11)
	v_cndmask_b32_e64 v194, v194, v196, s[44:45]
	v_pk_mul_f32 v[42:43], v[2:3], v[42:43] op_sel_hi:[0,1]
	v_pk_fma_f32 v[42:43], v[2:3], v[44:45], v[42:43] op_sel:[1,0,0] op_sel_hi:[1,1,1]
	v_add_f32_dpp v194, v194, v194 quad_perm:[1,0,3,2] row_mask:0xf bank_mask:0xf bound_ctrl:1
	v_pk_fma_f32 v[42:43], v[4:5], v[38:39], v[42:43] op_sel:[0,0,0] op_sel_hi:[0,1,1]
	v_pk_fma_f32 v[42:43], v[4:5], v[40:41], v[42:43] op_sel:[1,0,0] op_sel_hi:[1,1,1]
	v_add_f32_dpp v194, v194, v194 quad_perm:[2,3,0,1] row_mask:0xf bank_mask:0xf bound_ctrl:1
	v_pk_mul_f32 v[190:191], v[22:23], v[108:109] op_sel_hi:[1,0]
	v_pk_mul_f32 v[192:193], v[24:25], v[108:109] op_sel_hi:[1,0]
	v_cndmask_b32_e64 v143, v143, v194, s[50:51]
	v_add_f32_dpp v42, v42, v42 row_ror:8 row_mask:0xf bank_mask:0xf bound_ctrl:1
	v_add_f32_dpp v43, v43, v43 row_ror:8 row_mask:0xf bank_mask:0xf bound_ctrl:1
	v_pk_mul_f32 v[44:45], v[26:27], v[108:109] op_sel:[0,1] op_sel_hi:[1,1]
	v_add_f32_dpp v42, v42, v42 row_ror:4 row_mask:0xf bank_mask:0xf bound_ctrl:1
	v_add_f32_dpp v43, v43, v43 row_ror:4 row_mask:0xf bank_mask:0xf bound_ctrl:1
	v_pk_mul_f32 v[40:41], v[28:29], v[108:109] op_sel:[0,1] op_sel_hi:[1,1]
	v_add_f32_dpp v42, v42, v42 row_ror:2 row_mask:0xf bank_mask:0xf bound_ctrl:1
	v_add_f32_dpp v43, v43, v43 row_ror:2 row_mask:0xf bank_mask:0xf bound_ctrl:1
	s_nop 0
	v_add_f32_dpp v42, v42, v42 row_ror:1 row_mask:0xf bank_mask:0xf bound_ctrl:1
	v_add_f32_dpp v43, v43, v43 row_ror:1 row_mask:0xf bank_mask:0xf bound_ctrl:1
	v_pk_fma_f32 v[190:191], v[34:35], v[42:43], v[190:191] op_sel_hi:[1,0,1] neg_lo:[0,1,0] neg_hi:[0,1,0]
	v_pk_fma_f32 v[192:193], v[36:37], v[42:43], v[192:193] op_sel_hi:[1,0,1] neg_lo:[0,1,0] neg_hi:[0,1,0]
	v_fma_f32 v43, -v42, v110, v43
	v_pk_fma_f32 v[190:191], v[2:3], v[14:15], v[190:191]
	v_pk_fma_f32 v[192:193], v[4:5], v[16:17], v[192:193]
	v_fma_f32 v43, v108, v111, v43
	v_pk_mul_f32 v[6:7], v[190:191], v[6:7]
	v_pk_fma_f32 v[44:45], v[30:31], v[42:43], v[44:45] op_sel:[0,1,0] op_sel_hi:[1,1,1] neg_lo:[0,1,0] neg_hi:[0,1,0]
	v_pk_fma_f32 v[6:7], v[192:193], v[8:9], v[6:7]
	v_pk_fma_f32 v[40:41], v[32:33], v[42:43], v[40:41] op_sel:[0,1,0] op_sel_hi:[1,1,1] neg_lo:[0,1,0] neg_hi:[0,1,0]
	v_add_f32_e32 v194, v6, v7
	v_pk_fma_f32 v[2:3], v[190:191], v[18:19], v[44:45]
	v_pk_fma_f32 v[4:5], v[192:193], v[20:21], v[40:41]
	v_pk_mul_f32 v[10:11], v[2:3], v[10:11]
	v_pk_fma_f32 v[10:11], v[4:5], v[12:13], v[10:11]
	v_add_f32_e32 v195, v10, v11
	ds_read_b128 v[42:45], v140 offset:26368
	ds_read_b128 v[38:41], v140 offset:27200
	ds_read_b128 v[22:25], v140 offset:26112
	ds_read_b128 v[108:111], v141 offset:28816
	ds_read_b128 v[26:29], v140 offset:27728
	ds_read_b128 v[34:37], v140 offset:26624
	ds_read_b128 v[14:17], v140 offset:25856
	ds_read_b128 v[30:33], v140 offset:28240
	ds_read_b128 v[18:21], v140 offset:27472
	ds_read_b128 v[6:9], v140 offset:26880
	ds_read_b128 v[10:13], v140 offset:28496
	s_waitcnt lgkmcnt(11)
; __device__ __forceinline__ float row16_allsum(float x) { x = ROW_ROR_ADD(x, 8); x = ROW_ROR_ADD(x, 4); x = ROW_ROR_ADD(x, 2); x = ROW_ROR_ADD(x, 1); return x; }
; __device__ __forceinline__ float dot4(f32x4 a, f32x4 b) { return __builtin_fmaf(a[3], b[3], __builtin_fmaf(a[2], b[2], __builtin_fmaf(a[1], b[1], a[0] * b[0]))); }
; __device__ __forceinline__ void scan_phase(const Params& P, LAS unsigned char* lds, int tid, int wid, int lane) {
;     ...
;                 SC_LOADP(0, 0);
;                 for (int t0 = 0; t0 < nsteps; t0 += 16) {
;                     float ykeep = 0.f;
; #pragma unroll
;                     for (int u = 0; u < 8; ++u) {
;                         SC_LOADP((u + 1) & 1, t0 + 2 * u + 2);
;                         const int s = u & 1;
;                         float dA = dot4(S, kk0[s]), dB = dot4(S, wk0[s]);
;                         dA = row16_allsum(dA); dB = row16_allsum(dB);
;                         const float sa0 = -dA;
;                         const f32x4 S0 = S * w0[s] + (b0[s] * sa0 + kh0[s] * v0[s]);
;                         const float sa1 = -(dB + sa0 * bk[s].x + v0[s] * bk[s].y);
;                         const f32x4 S1 = S0 * w1[s] + (b1[s] * sa1 + kh1[s] * v1[s]);
;                         float y0 = dot4(S0, r0[s]), y1 = dot4(S1, r1[s]);
;                         y0 = row16_allsum(y0); y1 = row16_allsum(y1);
;                         ykeep = (jq == 2 * u) ? y0 : ykeep; ykeep = (jq == 2 * u + 1) ? y1 : ykeep;
;                         S = S1;
;                     }
;                     yb[(t0 + jq) * 16 + il] = ykeep;
	v_pk_mul_f32 v[152:153], v[2:3], v[152:153] op_sel_hi:[0,1]
	v_pk_fma_f32 v[152:153], v[2:3], v[154:155], v[152:153] op_sel:[1,0,0] op_sel_hi:[1,1,1]
	v_pk_fma_f32 v[152:153], v[4:5], v[164:165], v[152:153] op_sel:[0,0,0] op_sel_hi:[0,1,1]
	v_pk_fma_f32 v[152:153], v[4:5], v[166:167], v[152:153] op_sel:[1,0,0] op_sel_hi:[1,1,1]
	v_pk_mul_f32 v[190:191], v[148:149], v[184:185] op_sel_hi:[1,0]
	v_pk_mul_f32 v[192:193], v[150:151], v[184:185] op_sel_hi:[1,0]
	v_add_f32_dpp v152, v152, v152 row_ror:8 row_mask:0xf bank_mask:0xf bound_ctrl:1
	v_add_f32_dpp v153, v153, v153 row_ror:8 row_mask:0xf bank_mask:0xf bound_ctrl:1
	v_pk_mul_f32 v[154:155], v[172:173], v[184:185] op_sel:[0,1] op_sel_hi:[1,1]
	v_add_f32_dpp v152, v152, v152 row_ror:4 row_mask:0xf bank_mask:0xf bound_ctrl:1
	v_add_f32_dpp v153, v153, v153 row_ror:4 row_mask:0xf bank_mask:0xf bound_ctrl:1
	v_pk_mul_f32 v[166:167], v[174:175], v[184:185] op_sel:[0,1] op_sel_hi:[1,1]
	v_add_f32_dpp v152, v152, v152 row_ror:2 row_mask:0xf bank_mask:0xf bound_ctrl:1
	v_add_f32_dpp v153, v153, v153 row_ror:2 row_mask:0xf bank_mask:0xf bound_ctrl:1
	s_nop 0
	v_add_f32_dpp v152, v152, v152 row_ror:1 row_mask:0xf bank_mask:0xf bound_ctrl:1
	v_add_f32_dpp v153, v153, v153 row_ror:1 row_mask:0xf bank_mask:0xf bound_ctrl:1
	v_pk_fma_f32 v[190:191], v[156:157], v[152:153], v[190:191] op_sel_hi:[1,0,1] neg_lo:[0,1,0] neg_hi:[0,1,0]
	v_pk_fma_f32 v[192:193], v[158:159], v[152:153], v[192:193] op_sel_hi:[1,0,1] neg_lo:[0,1,0] neg_hi:[0,1,0]
	v_fma_f32 v153, -v152, v186, v153
	v_pk_fma_f32 v[190:191], v[2:3], v[144:145], v[190:191]
	v_pk_fma_f32 v[192:193], v[4:5], v[146:147], v[192:193]
	v_fma_f32 v153, v184, v187, v153
	v_pk_mul_f32 v[160:161], v[190:191], v[160:161]
	v_pk_fma_f32 v[154:155], v[176:177], v[152:153], v[154:155] op_sel:[0,1,0] op_sel_hi:[1,1,1] neg_lo:[0,1,0] neg_hi:[0,1,0]
	v_pk_fma_f32 v[160:161], v[192:193], v[162:163], v[160:161]
	v_pk_fma_f32 v[166:167], v[178:179], v[152:153], v[166:167] op_sel:[0,1,0] op_sel_hi:[1,1,1] neg_lo:[0,1,0] neg_hi:[0,1,0]
	v_add_f32_e32 v196, v160, v161
	v_pk_fma_f32 v[2:3], v[190:191], v[168:169], v[154:155]
	v_pk_fma_f32 v[4:5], v[192:193], v[170:171], v[166:167]
	v_pk_mul_f32 v[180:181], v[2:3], v[180:181]
	v_pk_fma_f32 v[180:181], v[4:5], v[182:183], v[180:181]
	v_add_f32_e32 v197, v180, v181
	v_add_f32_dpp v194, v194, v194 row_ror:8 row_mask:0xf bank_mask:0xf bound_ctrl:1
	v_add_f32_dpp v195, v195, v195 row_ror:8 row_mask:0xf bank_mask:0xf bound_ctrl:1
	v_add_f32_dpp v196, v196, v196 row_ror:8 row_mask:0xf bank_mask:0xf bound_ctrl:1
	v_add_f32_dpp v197, v197, v197 row_ror:8 row_mask:0xf bank_mask:0xf bound_ctrl:1
	v_cndmask_b32_e64 v194, v194, v195, s[42:43]
	v_cndmask_b32_e64 v196, v196, v197, s[42:43]
	s_and_b64 vcc, s[8:9], s[12:13]
	s_mov_b64 s[12:13], 0
	v_add_f32_dpp v194, v194, v194 row_half_mirror row_mask:0xf bank_mask:0xf bound_ctrl:1
	v_add_f32_dpp v196, v196, v196 row_half_mirror row_mask:0xf bank_mask:0xf bound_ctrl:1
	v_lshl_add_u32 v193, s37, 6, v255
	v_cndmask_b32_e64 v194, v194, v196, s[44:45]
	s_andn2_b64 vcc, exec, vcc
	v_add_u32_e32 v193, v193, v65
	v_add_f32_dpp v194, v194, v194 quad_perm:[1,0,3,2] row_mask:0xf bank_mask:0xf bound_ctrl:1
	s_mov_b32 s37, 16
	s_nop 0
	v_add_f32_dpp v194, v194, v194 quad_perm:[2,3,0,1] row_mask:0xf bank_mask:0xf bound_ctrl:1
	v_cndmask_b32_e64 v143, v143, v194, s[52:53]
	ds_write_b32 v193, v143
	s_cbranch_vccz .LBB0_881
	s_branch .LBB0_859
